# mixer critical-path shifting: latent items popped first also run the short conv of the item 16 places later (same tokens, next head); late-popped items skip the conv
# speedup vs baseline: 1.0099x; 1.0008x over previous
.LBB0_96:
	s_lshl_b32 s23, s38, 11
	s_and_b32 s22, s39, s37
	s_addk_i32 s23, 0x2000
	s_lshl_b32 s24, s38, 8
	s_and_b64 s[12:13], s[12:13], exec
	s_cselect_b32 s24, s23, s24
	s_lshl_b32 s25, s22, 7
	s_waitcnt lgkmcnt(0)
	s_add_u32 s12, s4, s29
	s_addc_u32 s13, s5, 0
	s_add_u32 s22, s12, 0x629c000
	s_addc_u32 s23, s13, 0
	global_load_dword v113, v192, s[12:13]
	global_load_dword v112, v133, s[22:23] offset:8
	s_mov_b32 s98, s35
	s_add_i32 s99, s35, 1
	s_cmpk_lt_i32 s37, 0x100
	s_cbranch_scc0 .Lconv_loop
	s_bitcmp1_b32 s37, 4
	s_cbranch_scc1 .Lconv_done
	s_add_i32 s99, s35, 2
.Lconv_loop:
	s_mov_b64 s[12:13], s[0:1]
	s_load_dwordx2 s[12:13], s[12:13], 0x68
	v_lshlrev_b32_e32 v0, 2, v40
	v_and_b32_e32 v0, 60, v0
	v_ashrrev_i32_e32 v13, 4, v40
	v_lshl_or_b32 v12, s98, 6, v0
	v_add_u32_e32 v29, s25, v13
	v_lshlrev_b32_e32 v0, 2, v12
	v_lshlrev_b32_e32 v132, 1, v12
	v_add_u32_e32 v18, s24, v29
	v_ashrrev_i32_e32 v19, 31, v18
	s_waitcnt lgkmcnt(0)
	s_add_u32 s12, s12, s6
	s_addc_u32 s13, s13, s7
	global_load_dwordx4 v[8:11], v0, s[12:13]
	global_load_dwordx4 v[4:7], v0, s[12:13] offset:1024
	s_nop 0
	global_load_dwordx4 v[0:3], v0, s[12:13] offset:2048
	v_lshl_add_u64 v[14:15], s[4:5], 0, v[132:133]
	v_lshlrev_b64 v[20:21], 9, v[18:19]
	s_mov_b64 s[12:13], 0xdea4400
	v_lshl_add_u64 v[16:17], v[14:15], 0, s[12:13]
	s_mov_b64 s[12:13], 0xe6a4400
	v_lshl_add_u64 v[22:23], v[14:15], 0, s[12:13]
	s_mov_b64 s[12:13], 0xd6a4400
	v_lshl_add_u64 v[24:25], v[14:15], 0, s[12:13]
	v_lshl_add_u64 v[16:17], v[16:17], 0, v[20:21]
	v_lshl_add_u64 v[22:23], v[22:23], 0, v[20:21]
	v_lshl_add_u64 v[24:25], v[24:25], 0, v[20:21]
	global_load_dwordx2 v[44:45], v[16:17], off offset:-512
	global_load_dwordx2 v[46:47], v[16:17], off
	global_load_dwordx2 v[48:49], v[16:17], off offset:512
	global_load_dwordx2 v[50:51], v[22:23], off offset:-512
	global_load_dwordx2 v[52:53], v[22:23], off
	global_load_dwordx2 v[54:55], v[22:23], off offset:512
	global_load_dwordx2 v[56:57], v[24:25], off
	v_lshl_add_u64 v[16:17], v[16:17], 0, s[76:77]
	v_lshl_add_u64 v[22:23], v[22:23], 0, s[76:77]
	v_lshl_add_u64 v[24:25], v[24:25], 0, s[76:77]
	global_load_dwordx2 v[58:59], v[16:17], off offset:-512
	global_load_dwordx2 v[60:61], v[16:17], off
	global_load_dwordx2 v[62:63], v[16:17], off offset:512
	global_load_dwordx2 v[64:65], v[22:23], off offset:-512
	global_load_dwordx2 v[66:67], v[22:23], off
	global_load_dwordx2 v[68:69], v[22:23], off offset:512
	global_load_dwordx2 v[70:71], v[24:25], off
	v_lshl_add_u64 v[16:17], v[16:17], 0, s[76:77]
	v_lshl_add_u64 v[22:23], v[22:23], 0, s[76:77]
	v_lshl_add_u64 v[24:25], v[24:25], 0, s[76:77]
	global_load_dwordx2 v[72:73], v[16:17], off offset:-512
	global_load_dwordx2 v[74:75], v[16:17], off
	global_load_dwordx2 v[76:77], v[16:17], off offset:512
	global_load_dwordx2 v[78:79], v[22:23], off offset:-512
	global_load_dwordx2 v[80:81], v[22:23], off
	global_load_dwordx2 v[82:83], v[22:23], off offset:512
	global_load_dwordx2 v[84:85], v[24:25], off
	v_lshl_add_u64 v[16:17], v[16:17], 0, s[76:77]
	v_lshl_add_u64 v[22:23], v[22:23], 0, s[76:77]
	v_lshl_add_u64 v[24:25], v[24:25], 0, s[76:77]
	global_load_dwordx2 v[86:87], v[16:17], off offset:-512
	global_load_dwordx2 v[88:89], v[16:17], off
	global_load_dwordx2 v[90:91], v[16:17], off offset:512
	global_load_dwordx2 v[92:93], v[22:23], off offset:-512
	global_load_dwordx2 v[94:95], v[22:23], off
	global_load_dwordx2 v[96:97], v[22:23], off offset:512
	global_load_dwordx2 v[98:99], v[24:25], off
	s_add_u32 s12, s4, 0xfea4400
	s_addc_u32 s13, s5, 0
	v_mov_b64_e32 v[26:27], s[12:13]
	v_mad_i64_i32 v[26:27], s[22:23], v18, s96, v[26:27]
	v_lshl_add_u64 v[26:27], v[26:27], 0, v[132:133]
	s_mov_b64 s[12:13], 0x14000
	v_add_u32_e32 v28, 0x60, v29
	s_waitcnt vmcnt(21)
	v_lshlrev_b32_e32 v100, 16, v44
	v_and_b32_e32 v101, 0xffff0000, v44
	v_lshlrev_b32_e32 v102, 16, v50
	v_and_b32_e32 v103, 0xffff0000, v50
	v_lshlrev_b32_e32 v104, 16, v45
	v_and_b32_e32 v105, 0xffff0000, v45
	v_lshlrev_b32_e32 v106, 16, v51
	v_and_b32_e32 v107, 0xffff0000, v51
	v_pk_mul_f32 v[30:31], v[100:101], v[102:103]
	v_pk_mul_f32 v[32:33], v[104:105], v[106:107]
	v_lshlrev_b32_e32 v100, 16, v46
	v_and_b32_e32 v101, 0xffff0000, v46
	v_lshlrev_b32_e32 v102, 16, v52
	v_and_b32_e32 v103, 0xffff0000, v52
	v_lshlrev_b32_e32 v104, 16, v47
	v_and_b32_e32 v105, 0xffff0000, v47
	v_lshlrev_b32_e32 v106, 16, v53
	v_and_b32_e32 v107, 0xffff0000, v53
	v_pk_mul_f32 v[34:35], v[100:101], v[102:103]
	v_pk_mul_f32 v[36:37], v[104:105], v[106:107]
	v_lshlrev_b32_e32 v100, 16, v48
	v_and_b32_e32 v101, 0xffff0000, v48
	v_lshlrev_b32_e32 v102, 16, v54
	v_and_b32_e32 v103, 0xffff0000, v54
	v_lshlrev_b32_e32 v104, 16, v49
	v_and_b32_e32 v105, 0xffff0000, v49
	v_lshlrev_b32_e32 v106, 16, v55
	v_and_b32_e32 v107, 0xffff0000, v55
	v_pk_mul_f32 v[108:109], v[100:101], v[102:103]
	v_pk_mul_f32 v[110:111], v[104:105], v[106:107]
	v_cmp_lt_i32_e32 vcc, 0, v29
	s_nop 1
	v_cndmask_b32_e32 v30, 0, v30, vcc
	v_cndmask_b32_e32 v31, 0, v31, vcc
	v_cndmask_b32_e32 v32, 0, v32, vcc
	v_cndmask_b32_e32 v33, 0, v33, vcc
	v_pk_mul_f32 v[32:33], v[10:11], v[32:33]
	v_pk_mul_f32 v[30:31], v[8:9], v[30:31]
	v_pk_fma_f32 v[32:33], v[6:7], v[36:37], v[32:33]
	v_pk_fma_f32 v[30:31], v[4:5], v[34:35], v[30:31]
	v_pk_fma_f32 v[30:31], v[0:1], v[108:109], v[30:31]
	v_pk_fma_f32 v[32:33], v[2:3], v[110:111], v[32:33]
	v_lshlrev_b32_e32 v100, 16, v56
	v_and_b32_e32 v101, 0xffff0000, v56
	v_lshlrev_b32_e32 v102, 16, v57
	v_and_b32_e32 v103, 0xffff0000, v57
	v_pk_mul_f32 v[32:33], v[32:33], v[102:103]
	v_pk_mul_f32 v[30:31], v[30:31], v[100:101]
	v_cvt_pk_bf16_f32 v30, v30, v31
	v_cvt_pk_bf16_f32 v31, v32, v33
	global_store_dwordx2 v[26:27], v[30:31], off offset:1024
	v_lshl_add_u64 v[26:27], v[26:27], 0, s[12:13]
	s_waitcnt vmcnt(14)
	v_lshlrev_b32_e32 v100, 16, v58
	v_and_b32_e32 v101, 0xffff0000, v58
	v_lshlrev_b32_e32 v102, 16, v64
	v_and_b32_e32 v103, 0xffff0000, v64
	v_lshlrev_b32_e32 v104, 16, v59
	v_and_b32_e32 v105, 0xffff0000, v59
	v_lshlrev_b32_e32 v106, 16, v65
	v_and_b32_e32 v107, 0xffff0000, v65
	v_pk_mul_f32 v[30:31], v[100:101], v[102:103]
	v_pk_mul_f32 v[32:33], v[104:105], v[106:107]
	v_lshlrev_b32_e32 v100, 16, v60
	v_and_b32_e32 v101, 0xffff0000, v60
	v_lshlrev_b32_e32 v102, 16, v66
	v_and_b32_e32 v103, 0xffff0000, v66
	v_lshlrev_b32_e32 v104, 16, v61
	v_and_b32_e32 v105, 0xffff0000, v61
	v_lshlrev_b32_e32 v106, 16, v67
	v_and_b32_e32 v107, 0xffff0000, v67
	v_pk_mul_f32 v[34:35], v[100:101], v[102:103]
	v_pk_mul_f32 v[36:37], v[104:105], v[106:107]
	v_lshlrev_b32_e32 v100, 16, v62
	v_and_b32_e32 v101, 0xffff0000, v62
	v_lshlrev_b32_e32 v102, 16, v68
	v_and_b32_e32 v103, 0xffff0000, v68
	v_lshlrev_b32_e32 v104, 16, v63
	v_and_b32_e32 v105, 0xffff0000, v63
	v_lshlrev_b32_e32 v106, 16, v69
	v_and_b32_e32 v107, 0xffff0000, v69
	v_pk_mul_f32 v[108:109], v[100:101], v[102:103]
	v_pk_mul_f32 v[110:111], v[104:105], v[106:107]
	v_pk_mul_f32 v[32:33], v[10:11], v[32:33]
	v_pk_mul_f32 v[30:31], v[8:9], v[30:31]
	v_pk_fma_f32 v[32:33], v[6:7], v[36:37], v[32:33]
	v_pk_fma_f32 v[30:31], v[4:5], v[34:35], v[30:31]
	v_pk_fma_f32 v[30:31], v[0:1], v[108:109], v[30:31]
	v_pk_fma_f32 v[32:33], v[2:3], v[110:111], v[32:33]
	v_lshlrev_b32_e32 v100, 16, v70
	v_and_b32_e32 v101, 0xffff0000, v70
	v_lshlrev_b32_e32 v102, 16, v71
	v_and_b32_e32 v103, 0xffff0000, v71
	v_pk_mul_f32 v[32:33], v[32:33], v[102:103]
	v_pk_mul_f32 v[30:31], v[30:31], v[100:101]
	v_cvt_pk_bf16_f32 v30, v30, v31
	v_cvt_pk_bf16_f32 v31, v32, v33
	global_store_dwordx2 v[26:27], v[30:31], off offset:1024
	v_lshl_add_u64 v[26:27], v[26:27], 0, s[12:13]
	s_waitcnt vmcnt(7)
	v_lshlrev_b32_e32 v100, 16, v72
	v_and_b32_e32 v101, 0xffff0000, v72
	v_lshlrev_b32_e32 v102, 16, v78
	v_and_b32_e32 v103, 0xffff0000, v78
	v_lshlrev_b32_e32 v104, 16, v73
	v_and_b32_e32 v105, 0xffff0000, v73
	v_lshlrev_b32_e32 v106, 16, v79
	v_and_b32_e32 v107, 0xffff0000, v79
	v_pk_mul_f32 v[30:31], v[100:101], v[102:103]
	v_pk_mul_f32 v[32:33], v[104:105], v[106:107]
	v_lshlrev_b32_e32 v100, 16, v74
	v_and_b32_e32 v101, 0xffff0000, v74
	v_lshlrev_b32_e32 v102, 16, v80
	v_and_b32_e32 v103, 0xffff0000, v80
	v_lshlrev_b32_e32 v104, 16, v75
	v_and_b32_e32 v105, 0xffff0000, v75
	v_lshlrev_b32_e32 v106, 16, v81
	v_and_b32_e32 v107, 0xffff0000, v81
	v_pk_mul_f32 v[34:35], v[100:101], v[102:103]
	v_pk_mul_f32 v[36:37], v[104:105], v[106:107]
	v_lshlrev_b32_e32 v100, 16, v76
	v_and_b32_e32 v101, 0xffff0000, v76
	v_lshlrev_b32_e32 v102, 16, v82
	v_and_b32_e32 v103, 0xffff0000, v82
	v_lshlrev_b32_e32 v104, 16, v77
	v_and_b32_e32 v105, 0xffff0000, v77
	v_lshlrev_b32_e32 v106, 16, v83
	v_and_b32_e32 v107, 0xffff0000, v83
	v_pk_mul_f32 v[108:109], v[100:101], v[102:103]
	v_pk_mul_f32 v[110:111], v[104:105], v[106:107]
	v_pk_mul_f32 v[32:33], v[10:11], v[32:33]
	v_pk_mul_f32 v[30:31], v[8:9], v[30:31]
	v_pk_fma_f32 v[32:33], v[6:7], v[36:37], v[32:33]
	v_pk_fma_f32 v[30:31], v[4:5], v[34:35], v[30:31]
	v_pk_fma_f32 v[30:31], v[0:1], v[108:109], v[30:31]
	v_pk_fma_f32 v[32:33], v[2:3], v[110:111], v[32:33]
	v_lshlrev_b32_e32 v100, 16, v84
	v_and_b32_e32 v101, 0xffff0000, v84
	v_lshlrev_b32_e32 v102, 16, v85
	v_and_b32_e32 v103, 0xffff0000, v85
	v_pk_mul_f32 v[32:33], v[32:33], v[102:103]
	v_pk_mul_f32 v[30:31], v[30:31], v[100:101]
	v_cvt_pk_bf16_f32 v30, v30, v31
	v_cvt_pk_bf16_f32 v31, v32, v33
	global_store_dwordx2 v[26:27], v[30:31], off offset:1024
	v_lshl_add_u64 v[26:27], v[26:27], 0, s[12:13]
	s_waitcnt vmcnt(0)
	v_lshlrev_b32_e32 v100, 16, v86
	v_and_b32_e32 v101, 0xffff0000, v86
	v_lshlrev_b32_e32 v102, 16, v92
	v_and_b32_e32 v103, 0xffff0000, v92
	v_lshlrev_b32_e32 v104, 16, v87
	v_and_b32_e32 v105, 0xffff0000, v87
	v_lshlrev_b32_e32 v106, 16, v93
	v_and_b32_e32 v107, 0xffff0000, v93
	v_pk_mul_f32 v[30:31], v[100:101], v[102:103]
	v_pk_mul_f32 v[32:33], v[104:105], v[106:107]
	v_lshlrev_b32_e32 v100, 16, v88
	v_and_b32_e32 v101, 0xffff0000, v88
	v_lshlrev_b32_e32 v102, 16, v94
	v_and_b32_e32 v103, 0xffff0000, v94
	v_lshlrev_b32_e32 v104, 16, v89
	v_and_b32_e32 v105, 0xffff0000, v89
	v_lshlrev_b32_e32 v106, 16, v95
	v_and_b32_e32 v107, 0xffff0000, v95
	v_pk_mul_f32 v[34:35], v[100:101], v[102:103]
	v_pk_mul_f32 v[36:37], v[104:105], v[106:107]
	v_lshlrev_b32_e32 v100, 16, v90
	v_and_b32_e32 v101, 0xffff0000, v90
	v_lshlrev_b32_e32 v102, 16, v96
	v_and_b32_e32 v103, 0xffff0000, v96
	v_lshlrev_b32_e32 v104, 16, v91
	v_and_b32_e32 v105, 0xffff0000, v91
	v_lshlrev_b32_e32 v106, 16, v97
	v_and_b32_e32 v107, 0xffff0000, v97
	v_pk_mul_f32 v[108:109], v[100:101], v[102:103]
	v_pk_mul_f32 v[110:111], v[104:105], v[106:107]
	v_cmp_gt_i32_e32 vcc, s36, v28
	s_nop 1
	v_cndmask_b32_e32 v108, 0, v108, vcc
	v_cndmask_b32_e32 v109, 0, v109, vcc
	v_cndmask_b32_e32 v110, 0, v110, vcc
	v_cndmask_b32_e32 v111, 0, v111, vcc
	v_pk_mul_f32 v[32:33], v[10:11], v[32:33]
	v_pk_mul_f32 v[30:31], v[8:9], v[30:31]
	v_pk_fma_f32 v[32:33], v[6:7], v[36:37], v[32:33]
	v_pk_fma_f32 v[30:31], v[4:5], v[34:35], v[30:31]
	v_pk_fma_f32 v[30:31], v[0:1], v[108:109], v[30:31]
	v_pk_fma_f32 v[32:33], v[2:3], v[110:111], v[32:33]
	v_lshlrev_b32_e32 v100, 16, v98
	v_and_b32_e32 v101, 0xffff0000, v98
	v_lshlrev_b32_e32 v102, 16, v99
	v_and_b32_e32 v103, 0xffff0000, v99
	v_pk_mul_f32 v[32:33], v[32:33], v[102:103]
	v_pk_mul_f32 v[30:31], v[30:31], v[100:101]
	v_cvt_pk_bf16_f32 v30, v30, v31
	v_cvt_pk_bf16_f32 v31, v32, v33
	global_store_dwordx2 v[26:27], v[30:31], off offset:1024
	s_add_i32 s98, s98, 1
	s_cmp_lt_u32 s98, s99
	s_cbranch_scc1 .Lconv_loop
.Lconv_done:
	s_add_u32 s12, s4, 0xfea4400
	s_addc_u32 s13, s5, 0
	v_ashrrev_i32_e32 v42, 6, v40
	v_cmp_lt_i32_e32 vcc, 3, v42
	s_nop 0
	v_readfirstlane_b32 s22, v42
	s_cmp_gt_i32 s22, 3
	s_cbranch_scc1 .Lprio_young
	s_setprio 0
	s_branch .Lprio_done
